# loader waves keep 14 of the 16 LoRA B-fragments in registers (1 - k_a folded into the k update as 1 + (a-1)*k_a, v143 renamed, fragment base moved)
# speedup vs baseline: 1.0371x; 1.0067x over previous
; __device__ __forceinline__ void phase_scan(const Params& p, LAS unsigned char* lds) {
;     ...
;         h16x8 mu_r8, mu_k8, mu_v8, mu_w8, mu_a8; f32x2 w0r[4], a0r[4], kkr[4], kar[4], omk[4], rkr[4];
; #pragma unroll
;         for (int e = 0; e < 8; ++e) { mu_r8[e] = (h16)mu[64 * h + c8 + e]; mu_k8[e] = (h16)mu[1024 + 64 * h + c8 + e]; mu_v8[e] = (h16)mu[2048 + 64 * h + c8 + e]; mu_w8[e] = (h16)mu[3072 + c8 + e]; mu_a8[e] = (h16)mu[3136 + c8 + e];
;             w0r[e >> 1][e & 1] = w0[c8 + e]; a0r[e >> 1][e & 1] = a0[c8 + e]; kkr[e >> 1][e & 1] = kkw[c8 + e]; kar[e >> 1][e & 1] = kaw[c8 + e]; omk[e >> 1][e & 1] = 1.f - kaw[c8 + e]; rkr[e >> 1][e & 1] = rkw[c8 + e]; }
;         f32x2 S01 = {0.f, 0.f}, S23 = {0.f, 0.f};
;         const int srow = 4 * (wave & 3) + (lane >> 4), j0 = 4 * (lane & 15);
;         const h16x8 z8 = {0, 0, 0, 0, 0, 0, 0, 0};
;         h16x8 pr, pk, pv, pw, pa, qr_, qk_, qv_, qw_, qa_;
;         const h16 *pcA, *pcB, *ppA, *ppB;
;         { const int t0_ = dir ? (SEQ - 1 - s_l) : s_l; pcA = PC + (size_t)(b * SEQ + t0_) * 3200 + c8 + 64 * h; pcB = pcA + 2048 - 64 * h;
;           const long po_ = (s_l > 0) ? (dir ? 3200 : -3200) : 0; ppA = pcA + po_; ppB = pcB + po_; }
;         const long cstride_ = dir ? -32 * 3200 : 32 * 3200;
;     ...
;         if (wave >= 4) { SCAN_LOAD_RAW(); if (s_l == 0) { qr_ = z8; qk_ = z8; qv_ = z8; qw_ = z8; qa_ = z8; } }
;         __syncthreads();
.LBB0_601:
	s_or_b64 exec, exec, s[10:11]
	s_waitcnt vmcnt(16)
	v_cvt_f16_f32_e32 v64, v64
	s_waitcnt vmcnt(13)
	v_cvt_f16_f32_e32 v68, v94
	v_cvt_f16_f32_e32 v0, v60
	s_waitcnt vmcnt(11)
	v_cvt_f16_f32_e32 v69, v98
	v_cvt_f16_f32_e32 v3, v90
	v_cvt_pk_f16_f32 v65, v65, v66
	v_cvt_pk_f16_f32 v90, v95, v96
	v_cvt_pk_f16_f32 v61, v61, v62
	v_pack_b32_f16 v62, v64, v65
	v_pack_b32_f16 v64, v68, v90
	v_cvt_pk_f16_f32 v68, v99, v100
	s_lshl_b64 s[48:49], s[12:13], 25
	s_lshl_b64 s[10:11], s[12:13], 20
	s_bfe_u32 s15, s78, 0x20003
	v_pack_b32_f16 v2, v0, v61
	v_cvt_pk_f16_f32 v0, v91, v92
	v_pack_b32_f16 v66, v69, v68
	v_cvt_pk_f16_f32 v69, v63, v74
	v_cvt_pk_f16_f32 v74, v93, v82
	s_waitcnt vmcnt(10)
	v_cvt_pk_f16_f32 v78, v101, v78
	v_cvt_pk_f16_f32 v75, v75, v76
	v_pack_b32_f16 v60, v3, v0
	v_alignbit_b32 v3, v69, v61, 16
	v_alignbit_b32 v61, v74, v0, 16
	v_cvt_pk_f16_f32 v0, v67, v70
	v_alignbit_b32 v67, v78, v68, 16
	v_alignbit_b32 v68, v75, v69, 16
	v_cvt_f16_f32_e32 v69, v77
	s_add_u32 s48, s68, s48
	s_addc_u32 s49, s69, s49
	s_add_u32 s34, s31, s10
	s_addc_u32 s35, s33, s11
	v_alignbit_b32 v69, v69, v75, 16
	v_cvt_f16_f32_e32 v75, v89
	s_add_u32 s54, s48, s20
	v_cvt_pk_f16_f32 v77, v79, v80
	s_addc_u32 s55, s49, 0
	s_lshl_b32 s14, s14, 2
	v_cvt_pk_f16_f32 v83, v83, v84
	v_cvt_pk_f16_f32 v84, v71, v72
	v_alignbit_b32 v76, v77, v78, 16
	v_cvt_f16_f32_e32 v71, v85
	v_cvt_f16_f32_e32 v73, v73
	v_cvt_f16_f32_e32 v78, v81
	s_add_u32 s52, s34, s14
	v_alignbit_b32 v63, v0, v65, 16
	v_cvt_pk_f16_f32 v82, v97, v86
	v_alignbit_b32 v72, v84, v0, 16
	v_cvt_pk_f16_f32 v0, v87, v88
	s_addc_u32 s53, s35, 0
	s_lshl_b32 s80, s15, 4
	s_lshl_b32 s14, s15, 5
	v_alignbit_b32 v70, v83, v74, 16
	v_alignbit_b32 v74, v0, v82, 16
	v_alignbit_b32 v75, v75, v0, 16
	v_or_b32_e32 v0, s15, v133
	s_add_u32 s14, s54, s14
	v_cmp_eq_u32_e64 s[10:11], s15, v176
	v_cmp_eq_u32_e64 s[12:13], 0, v0
	s_addc_u32 s15, s55, 0
	v_mov_b32_e32 v0, v1
	s_waitcnt vmcnt(2)
	v_pk_add_f32 v[154:155], v[48:49], 1.0 op_sel_hi:[1,0] neg_lo:[1,0] neg_hi:[1,0]
	v_pk_add_f32 v[156:157], v[50:51], 1.0 op_sel_hi:[1,0] neg_lo:[1,0] neg_hi:[1,0]
	v_alignbit_b32 v65, v82, v90, 16
	v_pk_add_f32 v[158:159], v[44:45], 1.0 op_sel_hi:[1,0] neg_lo:[1,0] neg_hi:[1,0]
	v_alignbit_b32 v71, v71, v83, 16
	v_alignbit_b32 v73, v73, v84, 16
	v_alignbit_b32 v77, v78, v77, 16
	v_pk_add_f32 v[160:161], v[46:47], 1.0 op_sel_hi:[1,0] neg_lo:[1,0] neg_hi:[1,0]
	s_waitcnt lgkmcnt(0)
	s_barrier
	s_mov_b32 s81, -1
	s_movk_i32 s82, 0xfc00
	v_mov_b32_e32 v162, v191
	v_mov_b32_e32 v145, v169
	v_mov_b64_e32 v[166:167], v[0:1]
	v_mov_b64_e32 v[164:165], v[0:1]
	s_cmp_eq_u64 s[0:1], 0
	s_cbranch_scc1 .Lscan_init
	v_mov_b32_e32 v170, v183
	ds_read_b128 v[132:135], v183 offset:64
	ds_read_b128 v[136:139], v183 offset:9280
	ds_read_b128 v[164:167], v183 offset:2368
	ds_read_b128 v[184:187], v183 offset:11584
	ds_read_b128 v[188:191], v183 offset:4672
	ds_read_b128 v[192:195], v183 offset:6976
	ds_read_b128 v[196:199], v183 offset:13888
	ds_read_b128 v[246:249], v183 offset:16192
	ds_read_b128 v[250:253], v183 offset:6912
	ds_read_b128 v[140:143], v183 offset:2304
	ds_read_b128 v[154:157], v183 offset:11520
	ds_read_b128 v[158:161], v183 offset:4608
	ds_read_b128 v[176:179], v183 offset:9216
	ds_read_b128 v[180:183], v183 offset:13824
	s_waitcnt lgkmcnt(0)
	s_branch .LBB0_604

; #define LDS_BAR() do { asm volatile("s_waitcnt lgkmcnt(0)" ::: "memory"); __builtin_amdgcn_s_barrier(); asm volatile("" ::: "memory"); } while (0)
; __device__ __forceinline__ void phase_scan(const Params& p, LAS unsigned char* lds) {
;     ...
;         for (int n = -1; n < SEQ / 32; ++n) {
;     ...
;             LDS_BAR();
;         }
.LBB0_603:
	s_or_b64 exec, exec, s[54:55]
	s_waitcnt lgkmcnt(0)
	s_barrier
	s_add_i32 s81, s81, 1
	s_addk_i32 s82, 0x200
	v_add_u32_e32 v145, 32, v145
	s_cmpk_eq_i32 s81, 0x100
	v_subrev_u32_e32 v162, 32, v162
	s_cbranch_scc1 .LBB0_620

; #define LAS __attribute__((address_space(3)))
; #define SCAN_LOAD(chn) SCAN_LOAD_RAW()
; __device__ __forceinline__ void phase_scan(const Params& p, LAS unsigned char* lds) {
;     ...
;                     { unsigned m1u_ = 0xBC00BC00u; asm volatile("" : "+s"(m1u_));
;                       typedef unsigned u32x4_ __attribute__((ext_vector_type(4))); const u32x4_ m1v_ = {m1u_, m1u_, m1u_, m1u_}; const h16x8 m1_ = __builtin_bit_cast(h16x8, m1v_);
;                       const h16x8 r8 = pr + mu_r8 * (pr * m1_ + qr_), k8 = pk + mu_k8 * (pk * m1_ + qk_), v8 = pv + mu_v8 * (pv * m1_ + qv_);
;                       const h16x8 w8 = pw + mu_w8 * (pw * m1_ + qw_), a8 = pa + mu_a8 * (pa * m1_ + qa_);
;                       h16x8 tw8;
; #pragma unroll
;                       for (int pi = 0; pi < 4; ++pi) { qr[pi] = (f32x2){(float)r8[2 * pi], (float)r8[2 * pi + 1]}; qk[pi] = (f32x2){(float)k8[2 * pi], (float)k8[2 * pi + 1]};
;                           qv[2 * pi] = (float)v8[2 * pi]; qv[2 * pi + 1] = (float)v8[2 * pi + 1];
;                           const f32x2 tx = (f32x2){(float)w8[2 * pi], (float)w8[2 * pi + 1]} * 2.8853900817779268f;
;                           const f32x2 dn = (f32x2){__builtin_amdgcn_exp2f(tx[0]), __builtin_amdgcn_exp2f(tx[1])} + 1.f;
;                           const f32x2 th = (f32x2){__builtin_amdgcn_rcpf(dn[0]), __builtin_amdgcn_rcpf(dn[1])} * -2.f + 1.f;
;                           tw8[2 * pi] = (h16)th[0]; tw8[2 * pi + 1] = (h16)th[1]; }
;                       *(LAS h16x8*)(TWp + s_sub * 72 + c8) = tw8; *(LAS h16x8*)(QAp + s_sub * 72 + c8) = a8; }
;                     if (cn + 1 < SEQ / 32) SCAN_LOAD(cn + 1);
;                     LDS_WAIT();
;                     f32x4 accw[4], acca[4];
; #pragma unroll
;                     for (int ct = 0; ct < 4; ++ct) { accw[ct] = (f32x4){0.f, 0.f, 0.f, 0.f}; acca[ct] = (f32x4){0.f, 0.f, 0.f, 0.f}; }
; #pragma unroll
;                     for (int ks = 0; ks < 2; ++ks) {
;                         const h16x8 atw = *(const LAS h16x8*)(TWp + (lane & 7) * 72 + 32 * ks + 8 * (lane >> 4));
;                         const h16x8 aqa = *(const LAS h16x8*)(QAp + (lane & 7) * 72 + 32 * ks + 8 * (lane >> 4));
; #pragma unroll
;                         for (int ct = 0; ct < 4; ++ct) {
;                             const h16x8 bw = *(const LAS h16x8*)(w2T + (16 * ct + (lane & 15)) * 72 + 32 * ks + 8 * (lane >> 4));
.LBB0_609:
.LBB0_610:
	s_waitcnt lgkmcnt(0)
	v_pk_fma_f16 v222, v95, s14, v99
	v_pk_fma_f16 v218, v96, s14, v100
	v_pk_fma_f16 v219, v97, s14, v101
	ds_read_b128 v[126:129], v173 offset:18432
	ds_read_b128 v[202:205], v173 offset:19584
	ds_read_b128 v[206:209], v170
	v_pk_fma_f16 v0, v94, s14, v98
	v_pk_fma_f16 v242, v69, v219, v97
	v_pk_fma_f16 v238, v68, v218, v96
	v_pk_fma_f16 v239, v3, v222, v95
	ds_read_b128 v[230:233], v170 offset:16128
	ds_read_b128 v[234:237], v173 offset:18496
	ds_read_b128 v[226:229], v173 offset:19648
	s_waitcnt lgkmcnt(3)
	v_mfma_f32_16x16x32_f16 v[206:209], v[126:129], v[206:209], 0
	v_pk_fma_f16 v0, v2, v0, v94
	v_pk_fma_f16 v94, v86, s14, v90
	v_pk_fma_f16 v95, v87, s14, v91
	v_mfma_f32_16x16x32_f16 v[210:213], v[202:205], v[176:179], 0
	v_pk_fma_f16 v240, v61, v95, v87
	v_cvt_f32_f16_sdwa v87, v0 dst_sel:DWORD dst_unused:UNUSED_PAD src0_sel:WORD_1
	s_bitcmp1_b32 s81, 0
	v_mfma_f32_16x16x32_f16 v[214:217], v[126:129], v[140:143], 0
	s_cselect_b32 s15, 0, 0xa800
	s_add_i32 s15, s15, 0
	v_mfma_f32_16x16x32_f16 v[96:99], v[202:205], v[154:157], 0
	v_pk_fma_f16 v100, v88, s14, v92
	v_pk_fma_f16 v101, v89, s14, v93
	v_pk_fma_f16 v244, v70, v100, v88
	v_mfma_f32_16x16x32_f16 v[218:221], v[126:129], v[158:161], 0
	v_pk_fma_f16 v243, v71, v101, v89
	v_pk_fma_f16 v101, v60, v94, v86
	v_cvt_f32_f16_e32 v86, v0
	v_mfma_f32_16x16x32_f16 v[222:225], v[202:205], v[180:183], 0
	v_cvt_f32_f16_e32 v100, v101
	v_cvt_f32_f16_sdwa v101, v101 dst_sel:DWORD dst_unused:UNUSED_PAD src0_sel:WORD_1
	v_mfma_f32_16x16x32_f16 v[126:129], v[126:129], v[250:253], 0
	s_waitcnt lgkmcnt(2)
	v_mfma_f32_16x16x32_f16 v[202:205], v[202:205], v[230:233], 0
	s_waitcnt lgkmcnt(1)
	v_mfma_f32_16x16x32_f16 v[206:209], v[234:237], v[132:135], v[206:209]
	s_waitcnt lgkmcnt(0)
	v_mfma_f32_16x16x32_f16 v[210:213], v[226:229], v[136:139], v[210:213]
	v_mfma_f32_16x16x32_f16 v[214:217], v[234:237], v[164:167], v[214:217]
	v_cvt_f32_f16_e32 v88, v239
	v_cvt_f32_f16_sdwa v89, v239 dst_sel:DWORD dst_unused:UNUSED_PAD src0_sel:WORD_1
	s_nop 2
	s_nop 1
	v_cndmask_b32_e64 v0, v210, v206, s[4:5]
	s_waitcnt lgkmcnt(0)
	v_mfma_f32_16x16x32_f16 v[218:221], v[234:237], v[188:191], v[218:221]
	v_cndmask_b32_e64 v206, v212, v208, s[4:5]
	v_add_u32_e32 v208, 0x4800, v174
	v_mfma_f32_16x16x32_f16 v[96:99], v[226:229], v[184:187], v[96:99]
	v_cvt_f32_f16_e32 v94, v240
	v_cvt_f32_f16_sdwa v95, v240 dst_sel:DWORD dst_unused:UNUSED_PAD src0_sel:WORD_1
	s_waitcnt lgkmcnt(0)
	v_mfma_f32_16x16x32_f16 v[222:225], v[226:229], v[196:199], v[222:225]
	v_cvt_f32_f16_e32 v90, v238
	v_cvt_f32_f16_sdwa v91, v238 dst_sel:DWORD dst_unused:UNUSED_PAD src0_sel:WORD_1
	v_mfma_f32_16x16x32_f16 v[126:129], v[234:237], v[192:195], v[126:129]
	s_nop 0
	v_cndmask_b32_e64 v96, v96, v214, s[4:5]
	s_waitcnt lgkmcnt(0)
	v_cndmask_b32_e64 v93, v211, v207, s[4:5]
	s_waitcnt lgkmcnt(0)
	v_mfma_f32_16x16x32_f16 v[202:205], v[226:229], v[246:249], v[202:205]
	ds_write2_b32 v208, v0, v96 offset1:16
	v_cndmask_b32_e64 v0, v97, v215, s[4:5]
	ds_write2_b32 v208, v93, v0 offset0:64 offset1:80
	v_cndmask_b32_e64 v0, v98, v216, s[4:5]
	v_cndmask_b32_e64 v207, v213, v209, s[4:5]
	ds_write2_b32 v208, v206, v0 offset0:128 offset1:144
	v_cndmask_b32_e64 v0, v99, v217, s[4:5]
	ds_write2_b32 v208, v207, v0 offset0:192 offset1:208
	v_cndmask_b32_e64 v0, v222, v218, s[4:5]
	v_cndmask_b32_e64 v98, v202, v126, s[4:5]
	v_cndmask_b32_e64 v93, v223, v219, s[4:5]
	ds_write2_b32 v208, v0, v98 offset0:32 offset1:48
	v_cndmask_b32_e64 v0, v203, v127, s[4:5]
	v_cndmask_b32_e64 v96, v224, v220, s[4:5]
	ds_write2_b32 v208, v93, v0 offset0:96 offset1:112
	v_cndmask_b32_e64 v0, v204, v128, s[4:5]
	v_cndmask_b32_e64 v97, v225, v221, s[4:5]
	ds_write2_b32 v208, v96, v0 offset0:160 offset1:176
	v_cndmask_b32_e64 v0, v205, v129, s[4:5]
	ds_write2_b32 v208, v97, v0 offset0:224 offset1:240
	s_waitcnt lgkmcnt(0)
	ds_read_b128 v[126:129], v200 offset:20480
	ds_read_b128 v[206:209], v200 offset:20496
	v_pk_mul_f32 v[212:213], v[40:41], v[100:101]
	v_pk_mul_f32 v[218:219], v[42:43], v[94:95]
	ds_read_b128 v[96:99], v200 offset:18432
	ds_read_b128 v[202:205], v200 offset:18448
	s_waitcnt lgkmcnt(3)
	v_pk_add_f32 v[126:127], v[32:33], v[126:127]
	s_waitcnt lgkmcnt(2)
	v_pk_add_f32 v[208:209], v[30:31], v[208:209]
	v_pk_mul_f32 v[126:127], v[126:127], s[36:37] op_sel_hi:[1,0]
	v_cvt_f32_f16_e32 v230, v244
	v_exp_f32_e32 v126, v126
	v_exp_f32_e32 v127, v127
	v_cvt_f32_f16_sdwa v231, v244 dst_sel:DWORD dst_unused:UNUSED_PAD src0_sel:WORD_1
	v_pk_mul_f32 v[208:209], v[208:209], s[36:37] op_sel_hi:[1,0]
	v_cvt_f32_f16_e32 v210, v243
	v_pk_add_f32 v[126:127], v[126:127], 1.0 op_sel_hi:[1,0]
	v_exp_f32_e32 v208, v208
	v_rcp_f32_e32 v214, v126
	v_rcp_f32_e32 v215, v127
	v_exp_f32_e32 v209, v209
	v_cvt_f32_f16_sdwa v211, v243 dst_sel:DWORD dst_unused:UNUSED_PAD src0_sel:WORD_1
	s_waitcnt lgkmcnt(1)
; #define LAS __attribute__((address_space(3)))
; __device__ __forceinline__ void phase_scan(const Params& p, LAS unsigned char* lds) {
;     ...
;                     f32x2 kk[4], av_[4], kp[4], dec[4], kn2 = {0.f, 0.f}, sb2 = {0.f, 0.f};
; #pragma unroll
;                     for (int pi = 0; pi < 4; ++pi) {
;                         const f32x2 zw = (pi < 2 ? (f32x2){zw0[2 * pi], zw0[2 * pi + 1]} : (f32x2){zw1[2 * pi - 4], zw1[2 * pi - 3]}) + w0r[pi];
;                         const f32x2 za = (pi < 2 ? (f32x2){za0[2 * pi], za0[2 * pi + 1]} : (f32x2){za1[2 * pi - 4], za1[2 * pi - 3]}) + a0r[pi];
;                         const f32x2 tw_ = zw * -1.4426950408889634f, ta_ = za * -1.4426950408889634f;
;                         const f32x2 dw = (f32x2){__builtin_amdgcn_exp2f(tw_[0]), __builtin_amdgcn_exp2f(tw_[1])} + 1.f, da = (f32x2){__builtin_amdgcn_exp2f(ta_[0]), __builtin_amdgcn_exp2f(ta_[1])} + 1.f;
;                         const f32x2 sw = (f32x2){__builtin_amdgcn_rcpf(dw[0]), __builtin_amdgcn_rcpf(dw[1])} * -0.8750387749225136f;
;                         dec[pi] = (f32x2){__builtin_amdgcn_exp2f(sw[0]), __builtin_amdgcn_exp2f(sw[1])};
;                         av_[pi] = (f32x2){__builtin_amdgcn_rcpf(da[0]), __builtin_amdgcn_rcpf(da[1])};
;                         kk[pi] = qk[pi] * kkr[pi]; kn2 = kk[pi] * kk[pi] + kn2;
;                         kp[pi] = qk[pi] * (av_[pi] * kar[pi] + omk[pi]);
;                         sb2 = (qr[pi] * kp[pi]) * rkr[pi] + sb2; }
;                     const float kn = red8(kn2[0] + kn2[1]), sbn = red8(sb2[0] + sb2[1]);
;                     const float ninv = -rsqrtf(fmaxf(kn, 1e-12f));
;                     LAS float* dR = OPS + (cn & 1) * SET_F + s_l * 64 + c8;
; #pragma unroll
;                     for (int hf = 0; hf < 2; ++hf) {
;                         const f32x2 na0 = kk[2 * hf] * ninv, na1 = kk[2 * hf + 1] * ninv;
;                         const f32x2 nb0 = na0 * av_[2 * hf], nb1 = na1 * av_[2 * hf + 1];
;                         *(LAS f32x4*)(dR + 4 * hf) = (f32x4){qr[2 * hf][0], qr[2 * hf][1], qr[2 * hf + 1][0], qr[2 * hf + 1][1]};
;                         *(LAS f32x4*)(dR + 2048 + 4 * hf) = (f32x4){dec[2 * hf][0], dec[2 * hf][1], dec[2 * hf + 1][0], dec[2 * hf + 1][1]};
;                         *(LAS f32x4*)(dR + 4096 + 4 * hf) = (f32x4){kp[2 * hf][0], kp[2 * hf][1], kp[2 * hf + 1][0], kp[2 * hf + 1][1]};
	v_pk_add_f32 v[96:97], v[24:25], v[96:97]
	v_pk_add_f32 v[126:127], v[214:215], 1.0 op_sel_hi:[1,0] neg_lo:[0,1] neg_hi:[0,1]
	v_pk_fma_f32 v[126:127], v[48:49], v[126:127], 1.0 op_sel_hi:[1,1,0]
	v_pk_add_f32 v[98:99], v[26:27], v[98:99]
	v_pk_mul_f32 v[126:127], v[126:127], v[100:101]
	v_pk_add_f32 v[100:101], v[34:35], v[128:129]
	v_pk_mul_f32 v[128:129], v[126:127], v[86:87]
	v_pk_mul_f32 v[100:101], v[100:101], s[36:37] op_sel_hi:[1,0]
	v_pk_fma_f32 v[216:217], v[56:57], v[128:129], 0 op_sel_hi:[1,1,0]
	v_exp_f32_e32 v100, v100
	v_exp_f32_e32 v101, v101
	v_pk_mul_f32 v[128:129], v[218:219], v[218:219]
	v_pk_mul_f32 v[224:225], v[36:37], v[230:231]
	v_pk_fma_f32 v[220:221], v[212:213], v[212:213], v[128:129]
	v_pk_add_f32 v[100:101], v[100:101], 1.0 op_sel_hi:[1,0]
	v_pk_mul_f32 v[96:97], v[96:97], s[36:37] op_sel_hi:[1,0]
	v_rcp_f32_e32 v100, v100
	v_rcp_f32_e32 v101, v101
	v_pk_mul_f32 v[98:99], v[98:99], s[36:37] op_sel_hi:[1,0]
	v_pk_add_f32 v[208:209], v[208:209], 1.0 op_sel_hi:[1,0]
	v_exp_f32_e32 v96, v96
	v_pk_add_f32 v[128:129], v[100:101], 1.0 op_sel_hi:[1,0] neg_lo:[0,1] neg_hi:[0,1]
	v_pk_fma_f32 v[128:129], v[50:51], v[128:129], 1.0 op_sel_hi:[1,1,0]
	v_exp_f32_e32 v97, v97
	v_pk_mul_f32 v[128:129], v[128:129], v[94:95]
	v_pk_add_f32 v[94:95], v[28:29], v[206:207]
	v_pk_mul_f32 v[206:207], v[128:129], v[88:89]
	v_pk_mul_f32 v[94:95], v[94:95], s[36:37] op_sel_hi:[1,0]
	v_pk_fma_f32 v[216:217], v[58:59], v[206:207], v[216:217]
	v_exp_f32_e32 v94, v94
	v_exp_f32_e32 v95, v95
	v_exp_f32_e32 v98, v98
	v_exp_f32_e32 v99, v99
	v_pk_mul_f32 v[226:227], v[38:39], v[210:211]
	v_pk_add_f32 v[94:95], v[94:95], 1.0 op_sel_hi:[1,0]
	s_waitcnt lgkmcnt(0)
	v_pk_add_f32 v[202:203], v[20:21], v[202:203]
	v_rcp_f32_e32 v222, v94
	v_rcp_f32_e32 v223, v95
	v_pk_fma_f32 v[94:95], v[224:225], v[224:225], v[220:221]
	v_pk_add_f32 v[204:205], v[22:23], v[204:205]
	v_pk_fma_f32 v[94:95], v[226:227], v[226:227], v[94:95]
	v_pk_add_f32 v[206:207], v[222:223], 1.0 op_sel_hi:[1,0] neg_lo:[0,1] neg_hi:[0,1]
	v_pk_fma_f32 v[206:207], v[44:45], v[206:207], 1.0 op_sel_hi:[1,1,0]
	v_cvt_f32_f16_e32 v92, v242
	v_pk_mul_f32 v[206:207], v[206:207], v[230:231]
	v_cvt_f32_f16_sdwa v93, v242 dst_sel:DWORD dst_unused:UNUSED_PAD src0_sel:WORD_1
	v_pk_mul_f32 v[220:221], v[206:207], v[90:91]
	v_pk_mul_f32 v[202:203], v[202:203], s[36:37] op_sel_hi:[1,0]
	v_pk_fma_f32 v[216:217], v[52:53], v[220:221], v[216:217]
	v_rcp_f32_e32 v220, v208
	v_rcp_f32_e32 v221, v209
	v_pk_mul_f32 v[204:205], v[204:205], s[36:37] op_sel_hi:[1,0]
	v_add_f32_e32 v0, v94, v95
	v_exp_f32_e32 v202, v202
	v_exp_f32_e32 v203, v203
	v_exp_f32_e32 v204, v204
	v_exp_f32_e32 v205, v205
	v_add_f32_dpp v0, v0, v0 quad_perm:[1,0,3,2] row_mask:0xf bank_mask:0xf bound_ctrl:1
	v_pk_add_f32 v[96:97], v[96:97], 1.0 op_sel_hi:[1,0]
	v_pk_add_f32 v[98:99], v[98:99], 1.0 op_sel_hi:[1,0]
	v_pk_add_f32 v[208:209], v[220:221], 1.0 op_sel_hi:[1,0] neg_lo:[0,1] neg_hi:[0,1]
	v_pk_fma_f32 v[208:209], v[46:47], v[208:209], 1.0 op_sel_hi:[1,1,0]
	v_add_f32_dpp v0, v0, v0 quad_perm:[2,3,0,1] row_mask:0xf bank_mask:0xf bound_ctrl:1
	v_rcp_f32_e32 v96, v96
	v_rcp_f32_e32 v97, v97
	v_rcp_f32_e32 v98, v98
	v_rcp_f32_e32 v99, v99
	v_pk_mul_f32 v[208:209], v[208:209], v[210:211]
	v_add_f32_dpp v95, v0, v0 row_half_mirror row_mask:0xf bank_mask:0xf bound_ctrl:1
	v_pk_mul_f32 v[210:211], v[208:209], v[92:93]
	v_max_f32_e32 v95, 0x2b8cbccc, v95
	v_pk_add_f32 v[202:203], v[202:203], 1.0 op_sel_hi:[1,0]
	v_pk_add_f32 v[204:205], v[204:205], 1.0 op_sel_hi:[1,0]
	v_pk_fma_f32 v[210:211], v[54:55], v[210:211], v[216:217]
	v_rsq_f32_e32 v216, v95
	v_rcp_f32_e32 v202, v202
	v_rcp_f32_e32 v203, v203
	v_rcp_f32_e32 v204, v204
	v_rcp_f32_e32 v205, v205
	v_pk_mul_f32 v[96:97], v[96:97], s[38:39] op_sel_hi:[1,0]
	v_pk_mul_f32 v[98:99], v[98:99], s[38:39] op_sel_hi:[1,0]
	v_add3_u32 v95, s15, v175, v144
	v_exp_f32_e32 v96, v96
	v_exp_f32_e32 v97, v97
	v_exp_f32_e32 v98, v98
	v_exp_f32_e32 v99, v99
	v_add_u32_e32 v217, 0x8800, v95
	v_add_f32_e32 v0, v210, v211
	v_pk_mul_f32 v[210:211], v[212:213], v[216:217] op_sel_hi:[1,0] neg_lo:[0,1] neg_hi:[0,1]
	v_pk_mul_f32 v[212:213], v[218:219], v[216:217] op_sel_hi:[1,0] neg_lo:[0,1] neg_hi:[0,1]
	v_pk_mul_f32 v[202:203], v[202:203], s[38:39] op_sel_hi:[1,0]
	v_pk_mul_f32 v[204:205], v[204:205], s[38:39] op_sel_hi:[1,0]
	v_pk_mul_f32 v[100:101], v[212:213], v[100:101]
	s_waitcnt lgkmcnt(0)
	v_exp_f32_e32 v202, v202
	v_exp_f32_e32 v203, v203
	v_exp_f32_e32 v204, v204
	v_exp_f32_e32 v205, v205
	ds_write_b128 v95, v[86:89] offset:34816
	ds_write_b128 v95, v[96:99] offset:43008
	ds_write_b128 v95, v[126:129] offset:51200
	ds_write_b128 v95, v[210:213] offset:59392
	v_pk_mul_f32 v[86:87], v[210:211], v[214:215] neg_lo:[0,1] neg_hi:[0,1]
	v_xor_b32_e32 v88, 0x80000000, v100
	v_xor_b32_e32 v89, 0x80000000, v101
	v_add_f32_dpp v0, v0, v0 quad_perm:[1,0,3,2] row_mask:0xf bank_mask:0xf bound_ctrl:1
	ds_write_b128 v217, v[86:89] offset:32768
	v_pk_mul_f32 v[88:89], v[226:227], v[216:217] op_sel_hi:[1,0] neg_lo:[0,1] neg_hi:[0,1]
	v_add_f32_dpp v0, v0, v0 quad_perm:[2,3,0,1] row_mask:0xf bank_mask:0xf bound_ctrl:1
	v_mov_b32_e32 v94, 0
	v_pk_mul_f32 v[86:87], v[224:225], v[216:217] op_sel_hi:[1,0] neg_lo:[0,1] neg_hi:[0,1]
	v_pk_mul_f32 v[96:97], v[88:89], v[220:221]
	v_mov_b32_dpp v94, v0 row_half_mirror row_mask:0xf bank_mask:0xf
	ds_write_b128 v95, v[90:93] offset:34832
	ds_write_b128 v95, v[202:205] offset:43024
	ds_write_b128 v95, v[206:209] offset:51216
	ds_write_b128 v95, v[86:89] offset:59408
	v_pk_mul_f32 v[86:87], v[86:87], v[222:223] neg_lo:[0,1] neg_hi:[0,1]
	v_xor_b32_e32 v88, 0x80000000, v96
	v_xor_b32_e32 v89, 0x80000000, v97
	ds_write_b128 v217, v[86:89] offset:32784
	s_and_saveexec_b64 s[56:57], s[10:11]
	s_cbranch_execz .LBB0_612
	v_pk_fma_f16 v82, v78, s14, v82
	v_pk_fma_f16 v83, v79, s14, v83
	v_pk_fma_f16 v78, v62, v82, v78
	v_pk_fma_f16 v84, v80, s14, v84
	v_pk_fma_f16 v79, v63, v83, v79
	v_cvt_f32_f16_e32 v82, v78
	v_cvt_f32_f16_sdwa v78, v78 dst_sel:DWORD dst_unused:UNUSED_PAD src0_sel:WORD_1
	s_add_i32 s15, s15, 0x8800
	v_pk_fma_f16 v85, v81, s14, v85
	v_pk_fma_f16 v80, v72, v84, v80
	v_cvt_f32_f16_e32 v83, v79
	v_cvt_f32_f16_sdwa v79, v79 dst_sel:DWORD dst_unused:UNUSED_PAD src0_sel:WORD_1
	v_lshlrev_b32_e32 v86, 2, v169
	v_pk_fma_f16 v81, v73, v85, v81
	v_cvt_f32_f16_e32 v84, v80
	v_cvt_f32_f16_sdwa v80, v80 dst_sel:DWORD dst_unused:UNUSED_PAD src0_sel:WORD_1
	v_add3_u32 v86, s15, v201, v86
	v_cvt_f32_f16_e32 v85, v81
	v_cvt_f32_f16_sdwa v81, v81 dst_sel:DWORD dst_unused:UNUSED_PAD src0_sel:WORD_1
	v_add_u32_e32 v86, 0xa000, v86
	ds_write2_b32 v86, v82, v78 offset1:32
	ds_write2_b32 v86, v83, v79 offset0:64 offset1:96
	ds_write2_b32 v86, v84, v80 offset0:128 offset1:160
	ds_write2_b32 v86, v85, v81 offset0:192 offset1:224
; __device__ __forceinline__ void phase_scan(const Params& p, LAS unsigned char* lds) {
;     ...
;                     if (q == 0 && (lane & 7) == 0) SB[(size_t)(b * SEQ + t) * 16 + h] = sbn;
.LBB0_612:
	s_or_b64 exec, exec, s[56:57]
	s_and_saveexec_b64 s[56:57], s[12:13]
	s_cbranch_execz .LBB0_614
	v_subrev_u32_e32 v78, 64, v162
	v_cndmask_b32_e64 v78, v78, v145, s[8:9]
	v_add_u32_e32 v78, s79, v78
	v_ashrrev_i32_e32 v79, 31, v78
	v_lshlrev_b64 v[78:79], 6, v[78:79]
	v_add_f32_e32 v0, v0, v94
	v_lshl_add_u64 v[78:79], s[52:53], 0, v[78:79]
	global_store_dword v[78:79], v0, off

; #define LAS __attribute__((address_space(3)))
; #define SCAN_LOAD(chn) SCAN_LOAD_RAW()
; __device__ __forceinline__ void phase_scan(const Params& p, LAS unsigned char* lds) {
;     ...
;                     { unsigned m1u_ = 0xBC00BC00u; asm volatile("" : "+s"(m1u_));
;                       typedef unsigned u32x4_ __attribute__((ext_vector_type(4))); const u32x4_ m1v_ = {m1u_, m1u_, m1u_, m1u_}; const h16x8 m1_ = __builtin_bit_cast(h16x8, m1v_);
;                       const h16x8 r8 = pr + mu_r8 * (pr * m1_ + qr_), k8 = pk + mu_k8 * (pk * m1_ + qk_), v8 = pv + mu_v8 * (pv * m1_ + qv_);
;                       const h16x8 w8 = pw + mu_w8 * (pw * m1_ + qw_), a8 = pa + mu_a8 * (pa * m1_ + qa_);
;                       h16x8 tw8;
; #pragma unroll
;                       for (int pi = 0; pi < 4; ++pi) { qr[pi] = (f32x2){(float)r8[2 * pi], (float)r8[2 * pi + 1]}; qk[pi] = (f32x2){(float)k8[2 * pi], (float)k8[2 * pi + 1]};
;                           qv[2 * pi] = (float)v8[2 * pi]; qv[2 * pi + 1] = (float)v8[2 * pi + 1];
;                           const f32x2 tx = (f32x2){(float)w8[2 * pi], (float)w8[2 * pi + 1]} * 2.8853900817779268f;
;                           const f32x2 dn = (f32x2){__builtin_amdgcn_exp2f(tx[0]), __builtin_amdgcn_exp2f(tx[1])} + 1.f;
;                           const f32x2 th = (f32x2){__builtin_amdgcn_rcpf(dn[0]), __builtin_amdgcn_rcpf(dn[1])} * -2.f + 1.f;
;                           tw8[2 * pi] = (h16)th[0]; tw8[2 * pi + 1] = (h16)th[1]; }
;                       *(LAS h16x8*)(TWp + s_sub * 72 + c8) = tw8; *(LAS h16x8*)(QAp + s_sub * 72 + c8) = a8; }
;                     if (cn + 1 < SEQ / 32) SCAN_LOAD(cn + 1);
;                     LDS_WAIT();
;                     f32x4 accw[4], acca[4];
; #pragma unroll
;                     for (int ct = 0; ct < 4; ++ct) { accw[ct] = (f32x4){0.f, 0.f, 0.f, 0.f}; acca[ct] = (f32x4){0.f, 0.f, 0.f, 0.f}; }
; #pragma unroll
;                     for (int ks = 0; ks < 2; ++ks) {
;                         const h16x8 atw = *(const LAS h16x8*)(TWp + (lane & 7) * 72 + 32 * ks + 8 * (lane >> 4));
;                         const h16x8 aqa = *(const LAS h16x8*)(QAp + (lane & 7) * 72 + 32 * ks + 8 * (lane >> 4));
; #pragma unroll
;                         for (int ct = 0; ct < 4; ++ct) {
;                             const h16x8 bw = *(const LAS h16x8*)(w2T + (16 * ct + (lane & 15)) * 72 + 32 * ks + 8 * (lane >> 4));
.Lpb_609:
.Lpb_610:
	s_waitcnt lgkmcnt(0)
	v_pk_fma_f16 v222, v119, s14, v123
	v_pk_fma_f16 v218, v120, s14, v124
	v_pk_fma_f16 v219, v121, s14, v125
	ds_read_b128 v[126:129], v173 offset:18432
	ds_read_b128 v[202:205], v173 offset:19584
	ds_read_b128 v[206:209], v170
	v_pk_fma_f16 v0, v118, s14, v122
	v_pk_fma_f16 v242, v69, v219, v121
	v_pk_fma_f16 v238, v68, v218, v120
	v_pk_fma_f16 v239, v3, v222, v119
	ds_read_b128 v[230:233], v170 offset:16128
	ds_read_b128 v[234:237], v173 offset:18496
	ds_read_b128 v[226:229], v173 offset:19648
	s_waitcnt lgkmcnt(3)
	v_mfma_f32_16x16x32_f16 v[206:209], v[126:129], v[206:209], 0
	v_pk_fma_f16 v0, v2, v0, v118
	v_pk_fma_f16 v118, v110, s14, v114
	v_pk_fma_f16 v119, v111, s14, v115
	v_mfma_f32_16x16x32_f16 v[210:213], v[202:205], v[176:179], 0
	v_pk_fma_f16 v240, v61, v119, v111
	v_cvt_f32_f16_sdwa v111, v0 dst_sel:DWORD dst_unused:UNUSED_PAD src0_sel:WORD_1
	s_bitcmp1_b32 s81, 0
	v_mfma_f32_16x16x32_f16 v[214:217], v[126:129], v[140:143], 0
	s_cselect_b32 s15, 0, 0xa800
	s_add_i32 s15, s15, 0
	v_mfma_f32_16x16x32_f16 v[120:123], v[202:205], v[154:157], 0
	v_pk_fma_f16 v124, v112, s14, v116
	v_pk_fma_f16 v125, v113, s14, v117
	v_pk_fma_f16 v244, v70, v124, v112
	v_mfma_f32_16x16x32_f16 v[218:221], v[126:129], v[158:161], 0
	v_pk_fma_f16 v243, v71, v125, v113
	v_pk_fma_f16 v125, v60, v118, v110
	v_cvt_f32_f16_e32 v110, v0
	v_mfma_f32_16x16x32_f16 v[222:225], v[202:205], v[180:183], 0
	v_cvt_f32_f16_e32 v124, v125
	v_cvt_f32_f16_sdwa v125, v125 dst_sel:DWORD dst_unused:UNUSED_PAD src0_sel:WORD_1
	v_mfma_f32_16x16x32_f16 v[126:129], v[126:129], v[250:253], 0
	s_waitcnt lgkmcnt(2)
	v_mfma_f32_16x16x32_f16 v[202:205], v[202:205], v[230:233], 0
	s_waitcnt lgkmcnt(1)
	v_mfma_f32_16x16x32_f16 v[206:209], v[234:237], v[132:135], v[206:209]
	s_waitcnt lgkmcnt(0)
	v_mfma_f32_16x16x32_f16 v[210:213], v[226:229], v[136:139], v[210:213]
	v_mfma_f32_16x16x32_f16 v[214:217], v[234:237], v[164:167], v[214:217]
	v_cvt_f32_f16_e32 v112, v239
	v_cvt_f32_f16_sdwa v113, v239 dst_sel:DWORD dst_unused:UNUSED_PAD src0_sel:WORD_1
	s_nop 2
	s_nop 1
	v_cndmask_b32_e64 v0, v210, v206, s[4:5]
	s_waitcnt lgkmcnt(0)
	v_mfma_f32_16x16x32_f16 v[218:221], v[234:237], v[188:191], v[218:221]
	v_cndmask_b32_e64 v206, v212, v208, s[4:5]
	v_add_u32_e32 v208, 0x4800, v174
	v_mfma_f32_16x16x32_f16 v[120:123], v[226:229], v[184:187], v[120:123]
	v_cvt_f32_f16_e32 v118, v240
	v_cvt_f32_f16_sdwa v119, v240 dst_sel:DWORD dst_unused:UNUSED_PAD src0_sel:WORD_1
	s_waitcnt lgkmcnt(0)
	v_mfma_f32_16x16x32_f16 v[222:225], v[226:229], v[196:199], v[222:225]
	v_cvt_f32_f16_e32 v114, v238
	v_cvt_f32_f16_sdwa v115, v238 dst_sel:DWORD dst_unused:UNUSED_PAD src0_sel:WORD_1
	v_mfma_f32_16x16x32_f16 v[126:129], v[234:237], v[192:195], v[126:129]
	s_nop 0
	v_cndmask_b32_e64 v120, v120, v214, s[4:5]
	s_waitcnt lgkmcnt(0)
	v_cndmask_b32_e64 v117, v211, v207, s[4:5]
	s_waitcnt lgkmcnt(0)
	v_mfma_f32_16x16x32_f16 v[202:205], v[226:229], v[246:249], v[202:205]
	ds_write2_b32 v208, v0, v120 offset1:16
	v_cndmask_b32_e64 v0, v121, v215, s[4:5]
	ds_write2_b32 v208, v117, v0 offset0:64 offset1:80
	v_cndmask_b32_e64 v0, v122, v216, s[4:5]
	v_cndmask_b32_e64 v207, v213, v209, s[4:5]
	ds_write2_b32 v208, v206, v0 offset0:128 offset1:144
	v_cndmask_b32_e64 v0, v123, v217, s[4:5]
	ds_write2_b32 v208, v207, v0 offset0:192 offset1:208
	v_cndmask_b32_e64 v0, v222, v218, s[4:5]
	v_cndmask_b32_e64 v122, v202, v126, s[4:5]
	v_cndmask_b32_e64 v117, v223, v219, s[4:5]
	ds_write2_b32 v208, v0, v122 offset0:32 offset1:48
	v_cndmask_b32_e64 v0, v203, v127, s[4:5]
	v_cndmask_b32_e64 v120, v224, v220, s[4:5]
	ds_write2_b32 v208, v117, v0 offset0:96 offset1:112
	v_cndmask_b32_e64 v0, v204, v128, s[4:5]
	v_cndmask_b32_e64 v121, v225, v221, s[4:5]
	ds_write2_b32 v208, v120, v0 offset0:160 offset1:176
	v_cndmask_b32_e64 v0, v205, v129, s[4:5]
	ds_write2_b32 v208, v121, v0 offset0:224 offset1:240
	s_waitcnt lgkmcnt(0)
	ds_read_b128 v[126:129], v200 offset:20480
	ds_read_b128 v[206:209], v200 offset:20496
	v_pk_mul_f32 v[212:213], v[40:41], v[124:125]
	v_pk_mul_f32 v[218:219], v[42:43], v[118:119]
	ds_read_b128 v[120:123], v200 offset:18432
	ds_read_b128 v[202:205], v200 offset:18448
	s_waitcnt lgkmcnt(3)
	v_pk_add_f32 v[126:127], v[32:33], v[126:127]
	s_waitcnt lgkmcnt(2)
	v_pk_add_f32 v[208:209], v[30:31], v[208:209]
	v_pk_mul_f32 v[126:127], v[126:127], s[36:37] op_sel_hi:[1,0]
	v_cvt_f32_f16_e32 v230, v244
	v_exp_f32_e32 v126, v126
	v_exp_f32_e32 v127, v127
	v_cvt_f32_f16_sdwa v231, v244 dst_sel:DWORD dst_unused:UNUSED_PAD src0_sel:WORD_1
	v_pk_mul_f32 v[208:209], v[208:209], s[36:37] op_sel_hi:[1,0]
	v_cvt_f32_f16_e32 v210, v243
	v_pk_add_f32 v[126:127], v[126:127], 1.0 op_sel_hi:[1,0]
	v_exp_f32_e32 v208, v208
	v_rcp_f32_e32 v214, v126
	v_rcp_f32_e32 v215, v127
	v_exp_f32_e32 v209, v209
	v_cvt_f32_f16_sdwa v211, v243 dst_sel:DWORD dst_unused:UNUSED_PAD src0_sel:WORD_1
	s_waitcnt lgkmcnt(1)
; #define LAS __attribute__((address_space(3)))
; __device__ __forceinline__ void phase_scan(const Params& p, LAS unsigned char* lds) {
;     ...
;                     f32x2 kk[4], av_[4], kp[4], dec[4], kn2 = {0.f, 0.f}, sb2 = {0.f, 0.f};
; #pragma unroll
;                     for (int pi = 0; pi < 4; ++pi) {
;                         const f32x2 zw = (pi < 2 ? (f32x2){zw0[2 * pi], zw0[2 * pi + 1]} : (f32x2){zw1[2 * pi - 4], zw1[2 * pi - 3]}) + w0r[pi];
;                         const f32x2 za = (pi < 2 ? (f32x2){za0[2 * pi], za0[2 * pi + 1]} : (f32x2){za1[2 * pi - 4], za1[2 * pi - 3]}) + a0r[pi];
;                         const f32x2 tw_ = zw * -1.4426950408889634f, ta_ = za * -1.4426950408889634f;
;                         const f32x2 dw = (f32x2){__builtin_amdgcn_exp2f(tw_[0]), __builtin_amdgcn_exp2f(tw_[1])} + 1.f, da = (f32x2){__builtin_amdgcn_exp2f(ta_[0]), __builtin_amdgcn_exp2f(ta_[1])} + 1.f;
;                         const f32x2 sw = (f32x2){__builtin_amdgcn_rcpf(dw[0]), __builtin_amdgcn_rcpf(dw[1])} * -0.8750387749225136f;
;                         dec[pi] = (f32x2){__builtin_amdgcn_exp2f(sw[0]), __builtin_amdgcn_exp2f(sw[1])};
;                         av_[pi] = (f32x2){__builtin_amdgcn_rcpf(da[0]), __builtin_amdgcn_rcpf(da[1])};
;                         kk[pi] = qk[pi] * kkr[pi]; kn2 = kk[pi] * kk[pi] + kn2;
;                         kp[pi] = qk[pi] * (av_[pi] * kar[pi] + omk[pi]);
;                         sb2 = (qr[pi] * kp[pi]) * rkr[pi] + sb2; }
;                     const float kn = red8(kn2[0] + kn2[1]), sbn = red8(sb2[0] + sb2[1]);
;                     const float ninv = -rsqrtf(fmaxf(kn, 1e-12f));
;                     LAS float* dR = OPS + (cn & 1) * SET_F + s_l * 64 + c8;
; #pragma unroll
;                     for (int hf = 0; hf < 2; ++hf) {
;                         const f32x2 na0 = kk[2 * hf] * ninv, na1 = kk[2 * hf + 1] * ninv;
;                         const f32x2 nb0 = na0 * av_[2 * hf], nb1 = na1 * av_[2 * hf + 1];
;                         *(LAS f32x4*)(dR + 4 * hf) = (f32x4){qr[2 * hf][0], qr[2 * hf][1], qr[2 * hf + 1][0], qr[2 * hf + 1][1]};
;                         *(LAS f32x4*)(dR + 2048 + 4 * hf) = (f32x4){dec[2 * hf][0], dec[2 * hf][1], dec[2 * hf + 1][0], dec[2 * hf + 1][1]};
;                         *(LAS f32x4*)(dR + 4096 + 4 * hf) = (f32x4){kp[2 * hf][0], kp[2 * hf][1], kp[2 * hf + 1][0], kp[2 * hf + 1][1]};
	v_pk_add_f32 v[120:121], v[24:25], v[120:121]
	v_pk_add_f32 v[126:127], v[214:215], 1.0 op_sel_hi:[1,0] neg_lo:[0,1] neg_hi:[0,1]
	v_pk_fma_f32 v[126:127], v[48:49], v[126:127], 1.0 op_sel_hi:[1,1,0]
	v_pk_add_f32 v[122:123], v[26:27], v[122:123]
	v_pk_mul_f32 v[126:127], v[126:127], v[124:125]
	v_pk_add_f32 v[124:125], v[34:35], v[128:129]
	v_pk_mul_f32 v[128:129], v[126:127], v[110:111]
	v_pk_mul_f32 v[124:125], v[124:125], s[36:37] op_sel_hi:[1,0]
	v_pk_fma_f32 v[216:217], v[56:57], v[128:129], 0 op_sel_hi:[1,1,0]
	v_exp_f32_e32 v124, v124
	v_exp_f32_e32 v125, v125
	v_pk_mul_f32 v[128:129], v[218:219], v[218:219]
	v_pk_mul_f32 v[224:225], v[36:37], v[230:231]
	v_pk_fma_f32 v[220:221], v[212:213], v[212:213], v[128:129]
	v_pk_add_f32 v[124:125], v[124:125], 1.0 op_sel_hi:[1,0]
	v_pk_mul_f32 v[120:121], v[120:121], s[36:37] op_sel_hi:[1,0]
	v_rcp_f32_e32 v124, v124
	v_rcp_f32_e32 v125, v125
	v_pk_mul_f32 v[122:123], v[122:123], s[36:37] op_sel_hi:[1,0]
	v_pk_add_f32 v[208:209], v[208:209], 1.0 op_sel_hi:[1,0]
	v_exp_f32_e32 v120, v120
	v_pk_add_f32 v[128:129], v[124:125], 1.0 op_sel_hi:[1,0] neg_lo:[0,1] neg_hi:[0,1]
	v_pk_fma_f32 v[128:129], v[50:51], v[128:129], 1.0 op_sel_hi:[1,1,0]
	v_exp_f32_e32 v121, v121
	v_pk_mul_f32 v[128:129], v[128:129], v[118:119]
	v_pk_add_f32 v[118:119], v[28:29], v[206:207]
	v_pk_mul_f32 v[206:207], v[128:129], v[112:113]
	v_pk_mul_f32 v[118:119], v[118:119], s[36:37] op_sel_hi:[1,0]
	v_pk_fma_f32 v[216:217], v[58:59], v[206:207], v[216:217]
	v_exp_f32_e32 v118, v118
	v_exp_f32_e32 v119, v119
	v_exp_f32_e32 v122, v122
	v_exp_f32_e32 v123, v123
	v_pk_mul_f32 v[226:227], v[38:39], v[210:211]
	v_pk_add_f32 v[118:119], v[118:119], 1.0 op_sel_hi:[1,0]
	s_waitcnt lgkmcnt(0)
	v_pk_add_f32 v[202:203], v[20:21], v[202:203]
	v_rcp_f32_e32 v222, v118
	v_rcp_f32_e32 v223, v119
	v_pk_fma_f32 v[118:119], v[224:225], v[224:225], v[220:221]
	v_pk_add_f32 v[204:205], v[22:23], v[204:205]
	v_pk_fma_f32 v[118:119], v[226:227], v[226:227], v[118:119]
	v_pk_add_f32 v[206:207], v[222:223], 1.0 op_sel_hi:[1,0] neg_lo:[0,1] neg_hi:[0,1]
	v_pk_fma_f32 v[206:207], v[44:45], v[206:207], 1.0 op_sel_hi:[1,1,0]
	v_cvt_f32_f16_e32 v116, v242
	v_pk_mul_f32 v[206:207], v[206:207], v[230:231]
	v_cvt_f32_f16_sdwa v117, v242 dst_sel:DWORD dst_unused:UNUSED_PAD src0_sel:WORD_1
	v_pk_mul_f32 v[220:221], v[206:207], v[114:115]
	v_pk_mul_f32 v[202:203], v[202:203], s[36:37] op_sel_hi:[1,0]
	v_pk_fma_f32 v[216:217], v[52:53], v[220:221], v[216:217]
	v_rcp_f32_e32 v220, v208
	v_rcp_f32_e32 v221, v209
	v_pk_mul_f32 v[204:205], v[204:205], s[36:37] op_sel_hi:[1,0]
	v_add_f32_e32 v0, v118, v119
	v_exp_f32_e32 v202, v202
	v_exp_f32_e32 v203, v203
	v_exp_f32_e32 v204, v204
	v_exp_f32_e32 v205, v205
	v_add_f32_dpp v0, v0, v0 quad_perm:[1,0,3,2] row_mask:0xf bank_mask:0xf bound_ctrl:1
	v_pk_add_f32 v[120:121], v[120:121], 1.0 op_sel_hi:[1,0]
	v_pk_add_f32 v[122:123], v[122:123], 1.0 op_sel_hi:[1,0]
	v_pk_add_f32 v[208:209], v[220:221], 1.0 op_sel_hi:[1,0] neg_lo:[0,1] neg_hi:[0,1]
	v_pk_fma_f32 v[208:209], v[46:47], v[208:209], 1.0 op_sel_hi:[1,1,0]
	v_add_f32_dpp v0, v0, v0 quad_perm:[2,3,0,1] row_mask:0xf bank_mask:0xf bound_ctrl:1
	v_rcp_f32_e32 v120, v120
	v_rcp_f32_e32 v121, v121
	v_rcp_f32_e32 v122, v122
	v_rcp_f32_e32 v123, v123
	v_pk_mul_f32 v[208:209], v[208:209], v[210:211]
	v_add_f32_dpp v119, v0, v0 row_half_mirror row_mask:0xf bank_mask:0xf bound_ctrl:1
	v_pk_mul_f32 v[210:211], v[208:209], v[116:117]
	v_max_f32_e32 v119, 0x2b8cbccc, v119
	v_pk_add_f32 v[202:203], v[202:203], 1.0 op_sel_hi:[1,0]
	v_pk_add_f32 v[204:205], v[204:205], 1.0 op_sel_hi:[1,0]
	v_pk_fma_f32 v[210:211], v[54:55], v[210:211], v[216:217]
	v_rsq_f32_e32 v216, v119
	v_rcp_f32_e32 v202, v202
	v_rcp_f32_e32 v203, v203
	v_rcp_f32_e32 v204, v204
	v_rcp_f32_e32 v205, v205
	v_pk_mul_f32 v[120:121], v[120:121], s[38:39] op_sel_hi:[1,0]
	v_pk_mul_f32 v[122:123], v[122:123], s[38:39] op_sel_hi:[1,0]
	v_add3_u32 v119, s15, v175, v144
	v_exp_f32_e32 v120, v120
	v_exp_f32_e32 v121, v121
	v_exp_f32_e32 v122, v122
	v_exp_f32_e32 v123, v123
	v_add_u32_e32 v217, 0x8800, v119
	v_add_f32_e32 v0, v210, v211
	v_pk_mul_f32 v[210:211], v[212:213], v[216:217] op_sel_hi:[1,0] neg_lo:[0,1] neg_hi:[0,1]
	v_pk_mul_f32 v[212:213], v[218:219], v[216:217] op_sel_hi:[1,0] neg_lo:[0,1] neg_hi:[0,1]
	v_pk_mul_f32 v[202:203], v[202:203], s[38:39] op_sel_hi:[1,0]
	v_pk_mul_f32 v[204:205], v[204:205], s[38:39] op_sel_hi:[1,0]
	v_pk_mul_f32 v[124:125], v[212:213], v[124:125]
	s_waitcnt lgkmcnt(0)
	v_exp_f32_e32 v202, v202
	v_exp_f32_e32 v203, v203
	v_exp_f32_e32 v204, v204
	v_exp_f32_e32 v205, v205
	ds_write_b128 v119, v[110:113] offset:34816
	ds_write_b128 v119, v[120:123] offset:43008
	ds_write_b128 v119, v[126:129] offset:51200
	ds_write_b128 v119, v[210:213] offset:59392
	v_pk_mul_f32 v[110:111], v[210:211], v[214:215] neg_lo:[0,1] neg_hi:[0,1]
	v_xor_b32_e32 v112, 0x80000000, v124
	v_xor_b32_e32 v113, 0x80000000, v125
	v_add_f32_dpp v0, v0, v0 quad_perm:[1,0,3,2] row_mask:0xf bank_mask:0xf bound_ctrl:1
	ds_write_b128 v217, v[110:113] offset:32768
	v_pk_mul_f32 v[112:113], v[226:227], v[216:217] op_sel_hi:[1,0] neg_lo:[0,1] neg_hi:[0,1]
	v_add_f32_dpp v0, v0, v0 quad_perm:[2,3,0,1] row_mask:0xf bank_mask:0xf bound_ctrl:1
	v_mov_b32_e32 v118, 0
	v_pk_mul_f32 v[110:111], v[224:225], v[216:217] op_sel_hi:[1,0] neg_lo:[0,1] neg_hi:[0,1]
	v_pk_mul_f32 v[120:121], v[112:113], v[220:221]
	v_mov_b32_dpp v118, v0 row_half_mirror row_mask:0xf bank_mask:0xf
	ds_write_b128 v119, v[114:117] offset:34832
	ds_write_b128 v119, v[202:205] offset:43024
	ds_write_b128 v119, v[206:209] offset:51216
	ds_write_b128 v119, v[110:113] offset:59408
	v_pk_mul_f32 v[110:111], v[110:111], v[222:223] neg_lo:[0,1] neg_hi:[0,1]
	v_xor_b32_e32 v112, 0x80000000, v120
	v_xor_b32_e32 v113, 0x80000000, v121
	ds_write_b128 v217, v[110:113] offset:32784
	s_and_saveexec_b64 s[56:57], s[10:11]
	s_cbranch_execz .Lpb_612
	v_pk_fma_f16 v106, v102, s14, v106
	v_pk_fma_f16 v107, v103, s14, v107
	v_pk_fma_f16 v102, v62, v106, v102
	v_pk_fma_f16 v108, v104, s14, v108
	v_pk_fma_f16 v103, v63, v107, v103
	v_cvt_f32_f16_e32 v106, v102
	v_cvt_f32_f16_sdwa v102, v102 dst_sel:DWORD dst_unused:UNUSED_PAD src0_sel:WORD_1
	s_add_i32 s15, s15, 0x8800
	v_pk_fma_f16 v109, v105, s14, v109
	v_pk_fma_f16 v104, v72, v108, v104
	v_cvt_f32_f16_e32 v107, v103
	v_cvt_f32_f16_sdwa v103, v103 dst_sel:DWORD dst_unused:UNUSED_PAD src0_sel:WORD_1
	v_lshlrev_b32_e32 v110, 2, v169
	v_pk_fma_f16 v105, v73, v109, v105
	v_cvt_f32_f16_e32 v108, v104
	v_cvt_f32_f16_sdwa v104, v104 dst_sel:DWORD dst_unused:UNUSED_PAD src0_sel:WORD_1
	v_add3_u32 v110, s15, v201, v110
	v_cvt_f32_f16_e32 v109, v105
	v_cvt_f32_f16_sdwa v105, v105 dst_sel:DWORD dst_unused:UNUSED_PAD src0_sel:WORD_1
	v_add_u32_e32 v110, 0xa000, v110
	ds_write2_b32 v110, v106, v102 offset1:32
	ds_write2_b32 v110, v107, v103 offset0:64 offset1:96
	ds_write2_b32 v110, v108, v104 offset0:128 offset1:160
	ds_write2_b32 v110, v109, v105 offset0:192 offset1:224
; __device__ __forceinline__ void phase_scan(const Params& p, LAS unsigned char* lds) {
;     ...
;                     if (q == 0 && (lane & 7) == 0) SB[(size_t)(b * SEQ + t) * 16 + h] = sbn;
.Lpb_612:
	s_or_b64 exec, exec, s[56:57]
	s_and_saveexec_b64 s[56:57], s[12:13]
	s_cbranch_execz .Lpb_614
	v_subrev_u32_e32 v102, 64, v162
	v_cndmask_b32_e64 v102, v102, v145, s[8:9]
	v_add_u32_e32 v102, s79, v102
	v_ashrrev_i32_e32 v103, 31, v102
	v_lshlrev_b64 v[102:103], 6, v[102:103]
	v_add_f32_e32 v0, v0, v118
	v_lshl_add_u64 v[102:103], s[52:53], 0, v[102:103]
	global_store_dword v[102:103], v0, off

; template <int CTRL> __device__ __forceinline__ float dpp_f(float x) { return __int_as_float(__builtin_amdgcn_update_dpp(0, __float_as_int(x), CTRL, 0xf, 0xf, false)); }
; __device__ __forceinline__ void phase_scan(const Params& p, LAS unsigned char* lds) {
;     ...
;                             const float v = vq[u16 >> 2][u16 & 3];
;                             const f32x2 vv = {v, v};
;                             f32x2 pp = S01 * (f32x2){a_[0], a_[1]}; pp = S23 * (f32x2){a_[2], a_[3]} + pp;
;                             f32x2 yy = S01 * (f32x2){rp[0], rp[1]}; yy = S23 * (f32x2){rp[2], rp[3]} + yy;
;                             float sa = pp[0] + pp[1], y = yy[0] + yy[1];
;                             sa += dpp_f<0xB1>(sa); y += dpp_f<0xB1>(y);
;                             sa += dpp_f<0x4E>(sa); y += dpp_f<0x4E>(y);
;                             sa += dpp_f<0x141>(sa); y += dpp_f<0x141>(y);
;                             sa += dpp_f<0x140>(sa); y += dpp_f<0x140>(y);
;                             sY[((s - 1) & 31) * 16 + srow] = y;
;                             const f32x2 sv = {sa, sa};
;                             S01 = S01 * (f32x2){w_[0], w_[1]} + vv * (f32x2){k_[0], k_[1]};
;                             S23 = S23 * (f32x2){w_[2], w_[3]} + vv * (f32x2){k_[2], k_[3]};
;                             S01 = sv * (f32x2){b_[0], b_[1]} + S01;
;                             S23 = sv * (f32x2){b_[2], b_[3]} + S23;
;                             rp = r_;
;                             a_ = a_n; w_ = w_n; b_ = b_n; k_ = k_n; r_ = r_n;
;                         }
; #pragma unroll
;                         for (int u = 0; u < 4; ++u) vq[u] = vn[u];
;                     }
;                     { f32x2 yy = S01 * (f32x2){rp[0], rp[1]}; yy = S23 * (f32x2){rp[2], rp[3]} + yy; sY[31 * 16 + srow] = red16(yy[0] + yy[1]); }
;     ...
;         if (wave >= 4) SCAN_YSTORE(SEQ / 32 - 1);
.LBB0_620:
	s_mov_b64 s[10:11], 0
	s_cmp_eq_u64 s[0:1], 0
	s_cbranch_scc0 .LBB0_594
	s_setprio 3
	s_mov_b32 s14, 0xfff0fff
	s_mov_b32 s15, s14
	v_pk_mul_f32 v[114:115], v[166:167], v[22:23]
	v_pk_mul_f32 v[116:117], v[166:167], v[18:19]
	v_pk_fma_f32 v[114:115], v[164:165], v[24:25], v[114:115]
	v_pk_fma_f32 v[116:117], v[164:165], v[20:21], v[116:117]
	v_add_f32_e32 v122, v114, v115
	v_pk_mul_f32 v[118:119], v[110:111], v[34:35] op_sel:[1,0]
	v_add_f32_e32 v212, v116, v117
	v_add_f32_dpp v122, v122, v122 quad_perm:[1,0,3,2] row_mask:0xf bank_mask:0xf bound_ctrl:1
	v_pk_mul_f32 v[120:121], v[110:111], v[36:37] op_sel:[1,0]
	v_add_f32_dpp v204, v204, v204 row_mirror row_mask:0xf bank_mask:0xf bound_ctrl:1
	v_add_f32_dpp v122, v122, v122 quad_perm:[2,3,0,1] row_mask:0xf bank_mask:0xf bound_ctrl:1
	v_pk_fma_f32 v[166:167], v[166:167], v[26:27], v[118:119]
	v_add_f32_dpp v204, v212, v212 row_mirror row_mask:0xf bank_mask:0xc bound_ctrl:1
	v_add_f32_dpp v122, v122, v122 row_half_mirror row_mask:0xf bank_mask:0xf bound_ctrl:1
	v_pk_fma_f32 v[164:165], v[164:165], v[28:29], v[120:121]
	s_nop 0
	v_add_f32_dpp v122, v122, v122 row_mirror row_mask:0xf bank_mask:0xf bound_ctrl:1
	s_nop 0
	v_pk_fma_f32 v[166:167], v[30:31], v[122:123], v[166:167] op_sel_hi:[1,0,1]
	v_pk_fma_f32 v[164:165], v[32:33], v[122:123], v[164:165] op_sel_hi:[1,0,1]
	v_pk_mul_f32 v[114:115], v[166:167], v[42:43]
	v_pk_mul_f32 v[116:117], v[166:167], v[38:39]
	v_pk_fma_f32 v[114:115], v[164:165], v[44:45], v[114:115]
	v_pk_fma_f32 v[116:117], v[164:165], v[40:41], v[116:117]
	v_add_f32_e32 v122, v114, v115
	v_pk_mul_f32 v[118:119], v[112:113], v[54:55] op_sel_hi:[0,1]
	v_add_f32_e32 v213, v116, v117
	v_add_f32_dpp v122, v122, v122 quad_perm:[1,0,3,2] row_mask:0xf bank_mask:0xf bound_ctrl:1
	v_pk_mul_f32 v[120:121], v[112:113], v[56:57] op_sel_hi:[0,1]
	v_add_f32_dpp v205, v205, v205 row_mirror row_mask:0xf bank_mask:0xf bound_ctrl:1
	v_add_f32_dpp v122, v122, v122 quad_perm:[2,3,0,1] row_mask:0xf bank_mask:0xf bound_ctrl:1
	v_pk_fma_f32 v[166:167], v[166:167], v[46:47], v[118:119]
	v_add_f32_dpp v205, v213, v213 row_mirror row_mask:0xf bank_mask:0xc bound_ctrl:1
	v_add_f32_dpp v122, v122, v122 row_half_mirror row_mask:0xf bank_mask:0xf bound_ctrl:1
	v_pk_fma_f32 v[164:165], v[164:165], v[48:49], v[120:121]
	s_nop 0
	v_add_f32_dpp v122, v122, v122 row_mirror row_mask:0xf bank_mask:0xf bound_ctrl:1
	s_nop 0
	v_pk_fma_f32 v[166:167], v[50:51], v[122:123], v[166:167] op_sel_hi:[1,0,1]
	v_pk_fma_f32 v[164:165], v[52:53], v[122:123], v[164:165] op_sel_hi:[1,0,1]
	v_pk_mul_f32 v[114:115], v[166:167], v[62:63]
	v_pk_mul_f32 v[116:117], v[166:167], v[58:59]
	v_pk_fma_f32 v[114:115], v[164:165], v[64:65], v[114:115]
	v_pk_fma_f32 v[116:117], v[164:165], v[60:61], v[116:117]
	v_add_f32_e32 v122, v114, v115
	v_pk_mul_f32 v[118:119], v[112:113], v[74:75] op_sel:[1,0]
	v_add_f32_e32 v214, v116, v117
	v_add_f32_dpp v122, v122, v122 quad_perm:[1,0,3,2] row_mask:0xf bank_mask:0xf bound_ctrl:1
	v_pk_mul_f32 v[120:121], v[112:113], v[76:77] op_sel:[1,0]
	v_add_f32_dpp v206, v206, v206 row_mirror row_mask:0xf bank_mask:0xf bound_ctrl:1
	v_add_f32_dpp v122, v122, v122 quad_perm:[2,3,0,1] row_mask:0xf bank_mask:0xf bound_ctrl:1
	v_pk_fma_f32 v[166:167], v[166:167], v[66:67], v[118:119]
	v_add_f32_dpp v206, v214, v214 row_mirror row_mask:0xf bank_mask:0xc bound_ctrl:1
	v_add_f32_dpp v122, v122, v122 row_half_mirror row_mask:0xf bank_mask:0xf bound_ctrl:1
	v_pk_fma_f32 v[164:165], v[164:165], v[68:69], v[120:121]
	s_nop 0
	v_add_f32_dpp v122, v122, v122 row_mirror row_mask:0xf bank_mask:0xf bound_ctrl:1
	s_nop 0
	v_pk_fma_f32 v[166:167], v[70:71], v[122:123], v[166:167] op_sel_hi:[1,0,1]
	v_pk_fma_f32 v[164:165], v[72:73], v[122:123], v[164:165] op_sel_hi:[1,0,1]
	v_pk_mul_f32 v[116:117], v[166:167], v[78:79]
	s_nop 0
	v_pk_fma_f32 v[116:117], v[164:165], v[80:81], v[116:117]
	s_nop 0
	v_add_f32_e32 v215, v116, v117
	v_mov_b32_e32 v216, 0
	v_mov_b32_e32 v217, 0
	v_mov_b32_e32 v218, 0
	v_mov_b32_e32 v219, 0
	s_nop 1
	v_add_f32_dpp v207, v207, v207 row_mirror row_mask:0xf bank_mask:0xf bound_ctrl:1
	v_add_f32_dpp v207, v215, v215 row_mirror row_mask:0xf bank_mask:0xc bound_ctrl:1
	v_add_f32_dpp v208, v208, v208 row_mirror row_mask:0xf bank_mask:0xf bound_ctrl:1
	v_add_f32_dpp v208, v216, v216 row_mirror row_mask:0xf bank_mask:0xc bound_ctrl:1
	v_add_f32_dpp v209, v209, v209 row_mirror row_mask:0xf bank_mask:0xf bound_ctrl:1
	v_add_f32_dpp v209, v217, v217 row_mirror row_mask:0xf bank_mask:0xc bound_ctrl:1
	v_add_f32_dpp v210, v210, v210 row_mirror row_mask:0xf bank_mask:0xf bound_ctrl:1
	v_add_f32_dpp v210, v218, v218 row_mirror row_mask:0xf bank_mask:0xc bound_ctrl:1
	v_add_f32_dpp v211, v211, v211 row_mirror row_mask:0xf bank_mask:0xf bound_ctrl:1
	v_add_f32_dpp v211, v219, v219 row_mirror row_mask:0xf bank_mask:0xc bound_ctrl:1
	s_nop 1
	v_add_f32_dpp v204, v204, v204 row_half_mirror row_mask:0xf bank_mask:0xf bound_ctrl:1
	v_add_f32_dpp v205, v205, v205 row_half_mirror row_mask:0xf bank_mask:0xf bound_ctrl:1
	v_add_f32_dpp v206, v206, v206 row_half_mirror row_mask:0xf bank_mask:0xf bound_ctrl:1
	v_add_f32_dpp v207, v207, v207 row_half_mirror row_mask:0xf bank_mask:0xf bound_ctrl:1
	v_add_f32_dpp v204, v208, v208 row_half_mirror row_mask:0xf bank_mask:0xa bound_ctrl:1
	v_add_f32_dpp v205, v209, v209 row_half_mirror row_mask:0xf bank_mask:0xa bound_ctrl:1
	v_add_f32_dpp v206, v210, v210 row_half_mirror row_mask:0xf bank_mask:0xa bound_ctrl:1
	v_add_f32_dpp v207, v211, v211 row_half_mirror row_mask:0xf bank_mask:0xa bound_ctrl:1
	v_add_f32_dpp v204, v204, v204 quad_perm:[1,0,3,2] row_mask:0xf bank_mask:0xf bound_ctrl:1
	v_add_f32_dpp v205, v205, v205 quad_perm:[1,0,3,2] row_mask:0xf bank_mask:0xf bound_ctrl:1
	v_add_f32_dpp v206, v206, v206 quad_perm:[1,0,3,2] row_mask:0xf bank_mask:0xf bound_ctrl:1
	v_add_f32_dpp v207, v207, v207 quad_perm:[1,0,3,2] row_mask:0xf bank_mask:0xf bound_ctrl:1
	v_add_f32_dpp v204, v204, v204 quad_perm:[2,3,0,1] row_mask:0xf bank_mask:0xf bound_ctrl:1
	v_add_f32_dpp v205, v205, v205 quad_perm:[2,3,0,1] row_mask:0xf bank_mask:0xf bound_ctrl:1
	v_add_f32_dpp v206, v206, v206 quad_perm:[2,3,0,1] row_mask:0xf bank_mask:0xf bound_ctrl:1
	v_add_f32_dpp v207, v207, v207 quad_perm:[2,3,0,1] row_mask:0xf bank_mask:0xf bound_ctrl:1
	v_cndmask_b32_e64 v202, v204, v205, s[34:35]
	v_cndmask_b32_e64 v202, v202, v206, s[56:57]
	v_cndmask_b32_e64 v202, v202, v207, s[98:99]
	v_cvt_f16_f32_e32 v203, v202
	s_mov_b64 exec, s[14:15]
	global_store_short v[128:129], v203, off
	s_mov_b64 exec, -1
	v_lshl_add_u64 v[128:129], v[128:129], 0, s[100:101]
	s_setprio 0
	s_branch .LBB0_594
